# context-prefix adaLN-RMSNorm copy (phase 1) replaced by the hand-written ring loop: its serialised per-vector load-wait-store ladder removed
# baseline (speedup 1.0000x reference)
; __device__ __forceinline__ void norm_rows(const float* src, int nrows, const float* gam, const float* sc, const float* sh, bf16_t* dst, int tid) {
;   const int lane = tid & 63; const int gw = blockIdx.x * 8 + (tid >> 6), nw = gridDim.x * 8;
; #pragma unroll 1
;   for (int r0 = gw; r0 < nrows; r0 += 4 * nw) {
;     f32x4 v[4][8]; float ss[4]; int rr[4]; bool ok[4];
; #pragma unroll
;     for (int q = 0; q < 4; ++q) { const int r = r0 + q * nw; ok[q] = r < nrows; rr[q] = ok[q] ? r : r0; }
; #pragma unroll
;     for (int q = 0; q < 4; ++q) { const f32x4* xr = (const f32x4*)(src + (size_t)rr[q] * DM) + lane;
; #pragma unroll
;       for (int j = 0; j < 8; ++j) v[q][j] = xr[64 * j]; }
; #pragma unroll
;     for (int q = 0; q < 4; ++q) { float s = 0.f;
; #pragma unroll
;       for (int j = 0; j < 8; ++j) s += v[q][j][0] * v[q][j][0] + v[q][j][1] * v[q][j][1] + v[q][j][2] * v[q][j][2] + v[q][j][3] * v[q][j][3];
;       ss[q] = rsqrtf(wave_sum(s) * (1.0f / DM) + 1e-6f); }
; #pragma unroll
;     for (int j = 0; j < 8; ++j) {
;       const int c = 4 * (lane + 64 * j);
;       const f32x4 mul = *(const f32x4*)(gam + c) * (1.0f + *(const f32x4*)(sc + c)); const f32x4 add = *(const f32x4*)(sh + c);
; __device__ __forceinline__ void phase_norm(KP p, int ph, unsigned char* shm, int tid) {
;     ...
;   const float* gam = (ffn ? p->in[5] : p->in[4]) + l * DM;
;   const float* sh = modv + l * 12288 + (ffn ? 3 : 0) * DM; const float* sc = sh + DM;
;   norm_rows(ph == 1 ? p->in[0] : p->out, SEQ, gam, sc, sh, HA, tid);
;   if (ph == 1) norm_rows(p->in[2], CTXL, gam, modv + 24576 + DM, modv + 24576, HA + (size_t)SEQ * DM, tid);
.LBB0_399:
	s_or_b64 exec, exec, s[14:15]
	v_cmp_gt_i32_e32 vcc, s88, v132
	s_and_b64 s[6:7], s[4:5], vcc
	s_and_saveexec_b64 s[4:5], s[6:7]
	s_cbranch_execz .LBB0_450
	s_add_u32 s6, s0, 0x6c1a000
	v_and_b32_e32 v0, 63, v229
	s_addc_u32 s7, s1, 0
	v_lshlrev_b32_e32 v138, 4, v0
	v_lshlrev_b32_e32 v0, 3, v0
	v_mov_b32_e32 v1, v139
	s_add_u32 s10, s0, 0x6c18000
	v_lshl_add_u64 v[2:3], s[0:1], 0, v[0:1]
	s_mov_b64 s[12:13], 0xac21000
	s_addc_u32 s11, s1, 0
	v_lshl_add_u64 v[136:137], v[2:3], 0, s[12:13]
	v_or_b32_e32 v2, 0x400, v138
	v_mov_b32_e32 v3, v139
	v_lshl_add_u64 v[154:155], s[6:7], 0, v[2:3]
	v_lshl_add_u64 v[156:157], s[10:11], 0, v[2:3]
	v_or_b32_e32 v2, 0x800, v138
	v_lshl_add_u64 v[158:159], s[6:7], 0, v[2:3]
	v_lshl_add_u64 v[160:161], s[10:11], 0, v[2:3]
	v_or_b32_e32 v2, 0xc00, v138
	v_lshl_add_u64 v[162:163], s[6:7], 0, v[2:3]
	v_lshl_add_u64 v[164:165], s[10:11], 0, v[2:3]
	v_or_b32_e32 v2, 0x1000, v138
	v_lshl_add_u64 v[166:167], s[2:3], 0, v[2:3]
	v_lshl_add_u64 v[168:169], s[6:7], 0, v[2:3]
	v_lshl_add_u64 v[170:171], s[10:11], 0, v[2:3]
	v_or_b32_e32 v2, 0x1400, v138
	v_readlane_b32 s8, v254, 9
	v_lshl_add_u64 v[172:173], s[2:3], 0, v[2:3]
	v_lshl_add_u64 v[174:175], s[6:7], 0, v[2:3]
	v_lshl_add_u64 v[176:177], s[10:11], 0, v[2:3]
	v_or_b32_e32 v2, 0x1800, v138
	v_readlane_b32 s9, v254, 10
	v_lshl_add_u64 v[178:179], s[2:3], 0, v[2:3]
	v_lshl_add_u64 v[180:181], s[6:7], 0, v[2:3]
	v_lshl_add_u64 v[182:183], s[10:11], 0, v[2:3]
	v_or_b32_e32 v2, 0x1c00, v138
	s_load_dwordx2 s[8:9], s[8:9], 0x10
	v_lshl_add_u64 v[184:185], s[2:3], 0, v[2:3]
	v_lshl_add_u64 v[186:187], s[6:7], 0, v[2:3]
	v_lshl_add_u64 v[188:189], s[10:11], 0, v[2:3]
	v_lshlrev_b64 v[2:3], 12, v[132:133]
	v_or_b32_e32 v2, v2, v0
	v_lshl_add_u64 v[148:149], s[2:3], 0, v[138:139]
	v_lshl_add_u64 v[0:1], s[0:1], 0, v[2:3]
	s_mov_b64 s[2:3], 0xac21e00
	v_lshl_add_u64 v[190:191], v[0:1], 0, s[2:3]
	v_lshlrev_b64 v[0:1], 13, v[132:133]
	v_or_b32_e32 v0, v0, v138
	s_waitcnt lgkmcnt(0)
	v_lshl_add_u64 v[0:1], s[8:9], 0, v[0:1]
	s_mov_b64 s[2:3], 0x1c00
	v_lshl_add_u64 v[134:135], s[8:9], 0, v[138:139]
	v_lshl_add_u64 v[150:151], s[6:7], 0, v[138:139]
	v_lshl_add_u64 v[152:153], s[10:11], 0, v[138:139]
	v_lshl_add_u64 v[192:193], v[0:1], 0, s[2:3]
	s_mov_b64 s[2:3], 0
	v_mov_b32_e32 v133, v132
	s_mov_b64 s[8:9], 0x1000
	v_lshl_add_u64 v[218:219], v[148:149], 0, s[8:9]
	global_load_dwordx4 v[154:157], v[148:149], off
	global_load_dwordx4 v[158:161], v[148:149], off offset:1024
	global_load_dwordx4 v[162:165], v[148:149], off offset:2048
	global_load_dwordx4 v[166:169], v[148:149], off offset:3072
	global_load_dwordx4 v[170:173], v[218:219], off
	global_load_dwordx4 v[174:177], v[218:219], off offset:1024
	global_load_dwordx4 v[178:181], v[218:219], off offset:2048
	global_load_dwordx4 v[182:185], v[218:219], off offset:3072
	v_lshl_add_u64 v[218:219], v[152:153], 0, s[8:9]
	global_load_dwordx4 v[186:189], v[152:153], off
	global_load_dwordx4 v[190:193], v[152:153], off offset:1024
	global_load_dwordx4 v[194:197], v[152:153], off offset:2048
	global_load_dwordx4 v[198:201], v[152:153], off offset:3072
	global_load_dwordx4 v[202:205], v[218:219], off
	global_load_dwordx4 v[206:209], v[218:219], off offset:1024
	global_load_dwordx4 v[210:213], v[218:219], off offset:2048
	global_load_dwordx4 v[214:217], v[218:219], off offset:3072
	v_lshl_add_u64 v[218:219], v[150:151], 0, s[8:9]
	global_load_dwordx4 v[0:3], v[150:151], off
	global_load_dwordx4 v[4:7], v[150:151], off offset:1024
	global_load_dwordx4 v[8:11], v[150:151], off offset:2048
	global_load_dwordx4 v[12:15], v[150:151], off offset:3072
	global_load_dwordx4 v[16:19], v[218:219], off
	global_load_dwordx4 v[20:23], v[218:219], off offset:1024
	global_load_dwordx4 v[24:27], v[218:219], off offset:2048
	global_load_dwordx4 v[28:31], v[218:219], off offset:3072
	s_waitcnt vmcnt(0)
	v_pk_add_f32 v[0:1], v[0:1], 1.0 op_sel_hi:[1,0]
	v_pk_mul_f32 v[154:155], v[154:155], v[0:1]
	v_pk_add_f32 v[2:3], v[2:3], 1.0 op_sel_hi:[1,0]
	v_pk_mul_f32 v[156:157], v[156:157], v[2:3]
	v_pk_add_f32 v[4:5], v[4:5], 1.0 op_sel_hi:[1,0]
	v_pk_mul_f32 v[158:159], v[158:159], v[4:5]
	v_pk_add_f32 v[6:7], v[6:7], 1.0 op_sel_hi:[1,0]
	v_pk_mul_f32 v[160:161], v[160:161], v[6:7]
	v_pk_add_f32 v[8:9], v[8:9], 1.0 op_sel_hi:[1,0]
	v_pk_mul_f32 v[162:163], v[162:163], v[8:9]
	v_pk_add_f32 v[10:11], v[10:11], 1.0 op_sel_hi:[1,0]
	v_pk_mul_f32 v[164:165], v[164:165], v[10:11]
	v_pk_add_f32 v[12:13], v[12:13], 1.0 op_sel_hi:[1,0]
	v_pk_mul_f32 v[166:167], v[166:167], v[12:13]
	v_pk_add_f32 v[14:15], v[14:15], 1.0 op_sel_hi:[1,0]
	v_pk_mul_f32 v[168:169], v[168:169], v[14:15]
	v_pk_add_f32 v[16:17], v[16:17], 1.0 op_sel_hi:[1,0]
	v_pk_mul_f32 v[170:171], v[170:171], v[16:17]
	v_pk_add_f32 v[18:19], v[18:19], 1.0 op_sel_hi:[1,0]
	v_pk_mul_f32 v[172:173], v[172:173], v[18:19]
	v_pk_add_f32 v[20:21], v[20:21], 1.0 op_sel_hi:[1,0]
	v_pk_mul_f32 v[174:175], v[174:175], v[20:21]
	v_pk_add_f32 v[22:23], v[22:23], 1.0 op_sel_hi:[1,0]
	v_pk_mul_f32 v[176:177], v[176:177], v[22:23]
	v_pk_add_f32 v[24:25], v[24:25], 1.0 op_sel_hi:[1,0]
	v_pk_mul_f32 v[178:179], v[178:179], v[24:25]
	v_pk_add_f32 v[26:27], v[26:27], 1.0 op_sel_hi:[1,0]
	v_pk_mul_f32 v[180:181], v[180:181], v[26:27]
	v_pk_add_f32 v[28:29], v[28:29], 1.0 op_sel_hi:[1,0]
	v_pk_mul_f32 v[182:183], v[182:183], v[28:29]
	v_pk_add_f32 v[30:31], v[30:31], 1.0 op_sel_hi:[1,0]
	v_pk_mul_f32 v[184:185], v[184:185], v[30:31]
	v_mbcnt_lo_u32_b32 v153, -1, 0
	v_mbcnt_hi_u32_b32 v153, -1, v153
	v_lshlrev_b32_e32 v153, 2, v153
	v_xor_b32_e32 v140, 4, v153
	v_xor_b32_e32 v141, 8, v153
	v_xor_b32_e32 v142, 16, v153
; __device__ __forceinline__ int lane_fresh() { return lane_asm(); }
; __device__ __forceinline__ float shfl_xor_l(float v, int m, int lane) { return __int_as_float(__builtin_amdgcn_ds_bpermute((lane ^ m) << 2, __float_as_int(v))); }
; __device__ __forceinline__ float wave_sum(float v) {
;   const int lane = lane_fresh();
; #pragma unroll
;   for (int o = 1; o < 64; o <<= 1) v += shfl_xor_l(v, o, lane);
;   return v;
; __device__ __forceinline__ void norm_rows(const float* src, int nrows, const float* gam, const float* sc, const float* sh, bf16_t* dst, int tid) {
;     ...
;   for (int r0 = gw; r0 < nrows; r0 += 4 * nw) {
;     f32x4 v[4][8]; float ss[4]; int rr[4]; bool ok[4];
; #pragma unroll
;     for (int q = 0; q < 4; ++q) { const int r = r0 + q * nw; ok[q] = r < nrows; rr[q] = ok[q] ? r : r0; }
; #pragma unroll
;     for (int q = 0; q < 4; ++q) { const f32x4* xr = (const f32x4*)(src + (size_t)rr[q] * DM) + lane;
; #pragma unroll
;       for (int j = 0; j < 8; ++j) v[q][j] = xr[64 * j]; }
; #pragma unroll
;     for (int q = 0; q < 4; ++q) { float s = 0.f;
; #pragma unroll
;       for (int j = 0; j < 8; ++j) s += v[q][j][0] * v[q][j][0] + v[q][j][1] * v[q][j][1] + v[q][j][2] * v[q][j][2] + v[q][j][3] * v[q][j][3];
;       ss[q] = rsqrtf(wave_sum(s) * (1.0f / DM) + 1e-6f); }
	v_xor_b32_e32 v150, 32, v153
	v_xor_b32_e32 v151, 64, v153
	v_xor_b32_e32 v152, 0x80, v153
	s_nop 0
	v_readfirstlane_b32 s6, v133
	s_mov_b32 s7, s6
	s_mov_b32 s11, s6
	s_cmp_lt_i32 s7, 0x100
	s_cselect_b32 s10, s7, s11
	s_lshl_b32 s8, s10, 13
	s_add_u32 s8, s8, 0x1000
	s_mov_b32 s9, 0
	v_lshl_add_u64 v[244:245], v[134:135], 0, s[8:9]
	global_load_dwordx4 v[0:3], v[244:245], off offset:-4096
	global_load_dwordx4 v[4:7], v[244:245], off offset:-3072
	global_load_dwordx4 v[8:11], v[244:245], off offset:-2048
	global_load_dwordx4 v[12:15], v[244:245], off offset:-1024
	global_load_dwordx4 v[16:19], v[244:245], off
	global_load_dwordx4 v[20:23], v[244:245], off offset:1024
	global_load_dwordx4 v[24:27], v[244:245], off offset:2048
	global_load_dwordx4 v[28:31], v[244:245], off offset:3072
	s_add_i32 s7, s7, s82
	s_cmp_lt_i32 s7, 0x100
	s_cselect_b32 s10, s7, s11
	s_lshl_b32 s8, s10, 13
	s_add_u32 s8, s8, 0x1000
	s_mov_b32 s9, 0
	v_lshl_add_u64 v[246:247], v[134:135], 0, s[8:9]
	global_load_dwordx4 v[32:35], v[246:247], off offset:-4096
	global_load_dwordx4 v[36:39], v[246:247], off offset:-3072
	global_load_dwordx4 v[40:43], v[246:247], off offset:-2048
	global_load_dwordx4 v[44:47], v[246:247], off offset:-1024
	global_load_dwordx4 v[48:51], v[246:247], off
	global_load_dwordx4 v[52:55], v[246:247], off offset:1024
	global_load_dwordx4 v[56:59], v[246:247], off offset:2048
	global_load_dwordx4 v[60:63], v[246:247], off offset:3072
	s_add_i32 s7, s7, s82
	s_cmp_lt_i32 s7, 0x100
	s_cselect_b32 s10, s7, s11
	s_lshl_b32 s8, s10, 13
	s_add_u32 s8, s8, 0x1000
	s_mov_b32 s9, 0
	v_lshl_add_u64 v[248:249], v[134:135], 0, s[8:9]
	global_load_dwordx4 v[64:67], v[248:249], off offset:-4096
	global_load_dwordx4 v[68:71], v[248:249], off offset:-3072
	global_load_dwordx4 v[72:75], v[248:249], off offset:-2048
	global_load_dwordx4 v[76:79], v[248:249], off offset:-1024
	global_load_dwordx4 v[80:83], v[248:249], off
	global_load_dwordx4 v[84:87], v[248:249], off offset:1024
	global_load_dwordx4 v[88:91], v[248:249], off offset:2048
	global_load_dwordx4 v[92:95], v[248:249], off offset:3072
	s_add_i32 s7, s7, s82
	s_cmp_lt_i32 s7, 0x100
	s_cselect_b32 s10, s7, s11
	s_lshl_b32 s8, s10, 13
	s_add_u32 s8, s8, 0x1000
	s_mov_b32 s9, 0
	v_lshl_add_u64 v[250:251], v[134:135], 0, s[8:9]
	global_load_dwordx4 v[96:99], v[250:251], off offset:-4096
	global_load_dwordx4 v[100:103], v[250:251], off offset:-3072
	global_load_dwordx4 v[104:107], v[250:251], off offset:-2048
	global_load_dwordx4 v[108:111], v[250:251], off offset:-1024
	global_load_dwordx4 v[112:115], v[250:251], off
	global_load_dwordx4 v[116:119], v[250:251], off offset:1024
	global_load_dwordx4 v[120:123], v[250:251], off offset:2048
	global_load_dwordx4 v[124:127], v[250:251], off offset:3072
	s_add_i32 s7, s7, s82
	s_waitcnt vmcnt(24)
	v_pk_mul_f32 v[218:219], v[0:1], v[0:1]
	v_pk_fma_f32 v[218:219], v[2:3], v[2:3], v[218:219]
	v_pk_mul_f32 v[220:221], v[4:5], v[4:5]
	v_pk_fma_f32 v[220:221], v[6:7], v[6:7], v[220:221]
	v_pk_mul_f32 v[222:223], v[8:9], v[8:9]
	v_pk_fma_f32 v[222:223], v[10:11], v[10:11], v[222:223]
	v_pk_mul_f32 v[224:225], v[12:13], v[12:13]
	v_pk_fma_f32 v[224:225], v[14:15], v[14:15], v[224:225]
	v_pk_fma_f32 v[218:219], v[16:17], v[16:17], v[218:219]
	v_pk_fma_f32 v[218:219], v[18:19], v[18:19], v[218:219]
	v_pk_fma_f32 v[220:221], v[20:21], v[20:21], v[220:221]
	v_pk_fma_f32 v[220:221], v[22:23], v[22:23], v[220:221]
	v_pk_fma_f32 v[222:223], v[24:25], v[24:25], v[222:223]
	v_pk_fma_f32 v[222:223], v[26:27], v[26:27], v[222:223]
	v_pk_fma_f32 v[224:225], v[28:29], v[28:29], v[224:225]
	v_pk_fma_f32 v[224:225], v[30:31], v[30:31], v[224:225]
	v_pk_add_f32 v[218:219], v[218:219], v[220:221]
	v_pk_add_f32 v[222:223], v[222:223], v[224:225]
	v_pk_add_f32 v[218:219], v[218:219], v[222:223]
	v_add_f32_e32 v128, v218, v219
	ds_bpermute_b32 v129, v140, v128
	s_waitcnt lgkmcnt(0)
	v_add_f32_e32 v128, v128, v129
	ds_bpermute_b32 v129, v141, v128
	s_waitcnt lgkmcnt(0)
	v_add_f32_e32 v128, v128, v129
	ds_bpermute_b32 v129, v142, v128
	s_waitcnt lgkmcnt(0)
	v_add_f32_e32 v128, v128, v129
	ds_bpermute_b32 v129, v150, v128
	s_waitcnt lgkmcnt(0)
	v_add_f32_e32 v128, v128, v129
	ds_bpermute_b32 v129, v151, v128
	s_waitcnt lgkmcnt(0)
	v_add_f32_e32 v128, v128, v129
	ds_bpermute_b32 v129, v152, v128
	s_waitcnt lgkmcnt(0)
; __device__ __forceinline__ unsigned cvt_pk_bf16(float lo, float hi) { unsigned r; asm volatile("v_cvt_pk_bf16_f32 %0, %1, %2" : "=v"(r) : "v"(lo), "v"(hi)); return r; }
; __device__ __forceinline__ void norm_rows(const float* src, int nrows, const float* gam, const float* sc, const float* sh, bf16_t* dst, int tid) {
;     ...
;     for (int q = 0; q < 4; ++q) { const f32x4* xr = (const f32x4*)(src + (size_t)rr[q] * DM) + lane;
; #pragma unroll
;       for (int j = 0; j < 8; ++j) v[q][j] = xr[64 * j]; }
; #pragma unroll
;     for (int q = 0; q < 4; ++q) { float s = 0.f;
; #pragma unroll
;       for (int j = 0; j < 8; ++j) s += v[q][j][0] * v[q][j][0] + v[q][j][1] * v[q][j][1] + v[q][j][2] * v[q][j][2] + v[q][j][3] * v[q][j][3];
;       ss[q] = rsqrtf(wave_sum(s) * (1.0f / DM) + 1e-6f); }
; #pragma unroll
;     for (int j = 0; j < 8; ++j) {
;       const int c = 4 * (lane + 64 * j);
;       const f32x4 mul = *(const f32x4*)(gam + c) * (1.0f + *(const f32x4*)(sc + c)); const f32x4 add = *(const f32x4*)(sh + c);
; #pragma unroll
;       for (int q = 0; q < 4; ++q) if (ok[q]) {
;         const f32x4 h = v[q][j] * ss[q] * mul + add; u32x2 w; w.x = cvt_pk_bf16(h[0], h[1]); w.y = cvt_pk_bf16(h[2], h[3]);
;         ((u32x2*)(dst + (size_t)rr[q] * DM) + lane)[64 * j] = w;
;       }
;     }
	v_add_f32_e32 v128, v128, v129
	v_fmamk_f32 v128, v128, 0x3a000000, v228
	v_mul_f32_e32 v129, 0x4b800000, v128
	v_cmp_gt_f32_e32 vcc, s67, v128
	s_nop 1
	v_cndmask_b32_e32 v128, v128, v129, vcc
	v_rsq_f32_e32 v128, v128
	s_nop 0
	v_mul_f32_e32 v129, 0x45800000, v128
	v_cndmask_b32_e32 v128, v128, v129, vcc
	s_lshl_b32 s8, s6, 12
	s_add_u32 s8, s8, 0x800
	s_mov_b32 s9, 0
	v_lshl_add_u64 v[230:231], v[136:137], 0, s[8:9]
	v_pk_mul_f32 v[0:1], v[0:1], v[128:129] op_sel_hi:[1,0]
	v_pk_fma_f32 v[0:1], v[0:1], v[154:155], v[186:187]
	v_pk_mul_f32 v[2:3], v[2:3], v[128:129] op_sel_hi:[1,0]
	v_pk_fma_f32 v[2:3], v[2:3], v[156:157], v[188:189]
	v_cvt_pk_bf16_f32 v0, v0, v1
	v_cvt_pk_bf16_f32 v1, v2, v3
	global_store_dwordx2 v[230:231], v[0:1], off offset:-2048
	v_pk_mul_f32 v[4:5], v[4:5], v[128:129] op_sel_hi:[1,0]
	v_pk_fma_f32 v[4:5], v[4:5], v[158:159], v[190:191]
	v_pk_mul_f32 v[6:7], v[6:7], v[128:129] op_sel_hi:[1,0]
	v_pk_fma_f32 v[6:7], v[6:7], v[160:161], v[192:193]
	v_cvt_pk_bf16_f32 v4, v4, v5
	v_cvt_pk_bf16_f32 v5, v6, v7
	global_store_dwordx2 v[230:231], v[4:5], off offset:-1536
	v_pk_mul_f32 v[8:9], v[8:9], v[128:129] op_sel_hi:[1,0]
	v_pk_fma_f32 v[8:9], v[8:9], v[162:163], v[194:195]
	v_pk_mul_f32 v[10:11], v[10:11], v[128:129] op_sel_hi:[1,0]
	v_pk_fma_f32 v[10:11], v[10:11], v[164:165], v[196:197]
	v_cvt_pk_bf16_f32 v8, v8, v9
	v_cvt_pk_bf16_f32 v9, v10, v11
	global_store_dwordx2 v[230:231], v[8:9], off offset:-1024
	v_pk_mul_f32 v[12:13], v[12:13], v[128:129] op_sel_hi:[1,0]
	v_pk_fma_f32 v[12:13], v[12:13], v[166:167], v[198:199]
	v_pk_mul_f32 v[14:15], v[14:15], v[128:129] op_sel_hi:[1,0]
	v_pk_fma_f32 v[14:15], v[14:15], v[168:169], v[200:201]
	v_cvt_pk_bf16_f32 v12, v12, v13
	v_cvt_pk_bf16_f32 v13, v14, v15
	global_store_dwordx2 v[230:231], v[12:13], off offset:-512
	v_pk_mul_f32 v[16:17], v[16:17], v[128:129] op_sel_hi:[1,0]
	v_pk_fma_f32 v[16:17], v[16:17], v[170:171], v[202:203]
	v_pk_mul_f32 v[18:19], v[18:19], v[128:129] op_sel_hi:[1,0]
	v_pk_fma_f32 v[18:19], v[18:19], v[172:173], v[204:205]
	v_cvt_pk_bf16_f32 v16, v16, v17
	v_cvt_pk_bf16_f32 v17, v18, v19
	global_store_dwordx2 v[230:231], v[16:17], off
	v_pk_mul_f32 v[20:21], v[20:21], v[128:129] op_sel_hi:[1,0]
	v_pk_fma_f32 v[20:21], v[20:21], v[174:175], v[206:207]
	v_pk_mul_f32 v[22:23], v[22:23], v[128:129] op_sel_hi:[1,0]
	v_pk_fma_f32 v[22:23], v[22:23], v[176:177], v[208:209]
	v_cvt_pk_bf16_f32 v20, v20, v21
	v_cvt_pk_bf16_f32 v21, v22, v23
	global_store_dwordx2 v[230:231], v[20:21], off offset:512
	v_pk_mul_f32 v[24:25], v[24:25], v[128:129] op_sel_hi:[1,0]
	v_pk_fma_f32 v[24:25], v[24:25], v[178:179], v[210:211]
	v_pk_mul_f32 v[26:27], v[26:27], v[128:129] op_sel_hi:[1,0]
	v_pk_fma_f32 v[26:27], v[26:27], v[180:181], v[212:213]
	v_cvt_pk_bf16_f32 v24, v24, v25
	v_cvt_pk_bf16_f32 v25, v26, v27
	global_store_dwordx2 v[230:231], v[24:25], off offset:1024
	v_pk_mul_f32 v[28:29], v[28:29], v[128:129] op_sel_hi:[1,0]
	v_pk_fma_f32 v[28:29], v[28:29], v[182:183], v[214:215]
	v_pk_mul_f32 v[30:31], v[30:31], v[128:129] op_sel_hi:[1,0]
	v_pk_fma_f32 v[30:31], v[30:31], v[184:185], v[216:217]
	v_cvt_pk_bf16_f32 v28, v28, v29
	v_cvt_pk_bf16_f32 v29, v30, v31
	global_store_dwordx2 v[230:231], v[28:29], off offset:1536
	s_add_i32 s6, s6, s82
	s_cmp_lt_i32 s6, 0x100
	s_cbranch_scc0 .Lnc_done
	s_cmp_lt_i32 s7, 0x100
	s_cselect_b32 s10, s7, s11
	s_lshl_b32 s8, s10, 13
	s_add_u32 s8, s8, 0x1000
	s_mov_b32 s9, 0
	v_lshl_add_u64 v[244:245], v[134:135], 0, s[8:9]
	global_load_dwordx4 v[0:3], v[244:245], off offset:-4096
	global_load_dwordx4 v[4:7], v[244:245], off offset:-3072
	global_load_dwordx4 v[8:11], v[244:245], off offset:-2048
	global_load_dwordx4 v[12:15], v[244:245], off offset:-1024
	global_load_dwordx4 v[16:19], v[244:245], off
	global_load_dwordx4 v[20:23], v[244:245], off offset:1024
	global_load_dwordx4 v[24:27], v[244:245], off offset:2048
	global_load_dwordx4 v[28:31], v[244:245], off offset:3072
	s_add_i32 s7, s7, s82
	s_waitcnt vmcnt(32)
	v_pk_mul_f32 v[218:219], v[32:33], v[32:33]
	v_pk_fma_f32 v[218:219], v[34:35], v[34:35], v[218:219]
	v_pk_mul_f32 v[220:221], v[36:37], v[36:37]
	v_pk_fma_f32 v[220:221], v[38:39], v[38:39], v[220:221]
	v_pk_mul_f32 v[222:223], v[40:41], v[40:41]
	v_pk_fma_f32 v[222:223], v[42:43], v[42:43], v[222:223]
	v_pk_mul_f32 v[224:225], v[44:45], v[44:45]
	v_pk_fma_f32 v[224:225], v[46:47], v[46:47], v[224:225]
	v_pk_fma_f32 v[218:219], v[48:49], v[48:49], v[218:219]
	v_pk_fma_f32 v[218:219], v[50:51], v[50:51], v[218:219]
	v_pk_fma_f32 v[220:221], v[52:53], v[52:53], v[220:221]
	v_pk_fma_f32 v[220:221], v[54:55], v[54:55], v[220:221]
	v_pk_fma_f32 v[222:223], v[56:57], v[56:57], v[222:223]
	v_pk_fma_f32 v[222:223], v[58:59], v[58:59], v[222:223]
	v_pk_fma_f32 v[224:225], v[60:61], v[60:61], v[224:225]
	v_pk_fma_f32 v[224:225], v[62:63], v[62:63], v[224:225]
	v_pk_add_f32 v[218:219], v[218:219], v[220:221]
	v_pk_add_f32 v[222:223], v[222:223], v[224:225]
	v_pk_add_f32 v[218:219], v[218:219], v[222:223]
	v_add_f32_e32 v128, v218, v219
	ds_bpermute_b32 v129, v140, v128
	s_waitcnt lgkmcnt(0)
	v_add_f32_e32 v128, v128, v129
	ds_bpermute_b32 v129, v141, v128
	s_waitcnt lgkmcnt(0)
	v_add_f32_e32 v128, v128, v129
	ds_bpermute_b32 v129, v142, v128
	s_waitcnt lgkmcnt(0)
	v_add_f32_e32 v128, v128, v129
	ds_bpermute_b32 v129, v150, v128
	s_waitcnt lgkmcnt(0)
	v_add_f32_e32 v128, v128, v129
	ds_bpermute_b32 v129, v151, v128
	s_waitcnt lgkmcnt(0)
	v_add_f32_e32 v128, v128, v129
	ds_bpermute_b32 v129, v152, v128
	s_waitcnt lgkmcnt(0)
; __device__ __forceinline__ unsigned cvt_pk_bf16(float lo, float hi) { unsigned r; asm volatile("v_cvt_pk_bf16_f32 %0, %1, %2" : "=v"(r) : "v"(lo), "v"(hi)); return r; }
; __device__ __forceinline__ void norm_rows(const float* src, int nrows, const float* gam, const float* sc, const float* sh, bf16_t* dst, int tid) {
;     ...
;     for (int q = 0; q < 4; ++q) { const f32x4* xr = (const f32x4*)(src + (size_t)rr[q] * DM) + lane;
; #pragma unroll
;       for (int j = 0; j < 8; ++j) v[q][j] = xr[64 * j]; }
; #pragma unroll
;     for (int q = 0; q < 4; ++q) { float s = 0.f;
; #pragma unroll
;       for (int j = 0; j < 8; ++j) s += v[q][j][0] * v[q][j][0] + v[q][j][1] * v[q][j][1] + v[q][j][2] * v[q][j][2] + v[q][j][3] * v[q][j][3];
;       ss[q] = rsqrtf(wave_sum(s) * (1.0f / DM) + 1e-6f); }
; #pragma unroll
;     for (int j = 0; j < 8; ++j) {
;       const int c = 4 * (lane + 64 * j);
;       const f32x4 mul = *(const f32x4*)(gam + c) * (1.0f + *(const f32x4*)(sc + c)); const f32x4 add = *(const f32x4*)(sh + c);
; #pragma unroll
;       for (int q = 0; q < 4; ++q) if (ok[q]) {
;         const f32x4 h = v[q][j] * ss[q] * mul + add; u32x2 w; w.x = cvt_pk_bf16(h[0], h[1]); w.y = cvt_pk_bf16(h[2], h[3]);
;         ((u32x2*)(dst + (size_t)rr[q] * DM) + lane)[64 * j] = w;
;       }
;     }
	v_add_f32_e32 v128, v128, v129
	v_fmamk_f32 v128, v128, 0x3a000000, v228
	v_mul_f32_e32 v129, 0x4b800000, v128
	v_cmp_gt_f32_e32 vcc, s67, v128
	s_nop 1
	v_cndmask_b32_e32 v128, v128, v129, vcc
	v_rsq_f32_e32 v128, v128
	s_nop 0
	v_mul_f32_e32 v129, 0x45800000, v128
	v_cndmask_b32_e32 v128, v128, v129, vcc
	s_lshl_b32 s8, s6, 12
	s_add_u32 s8, s8, 0x800
	s_mov_b32 s9, 0
	v_lshl_add_u64 v[230:231], v[136:137], 0, s[8:9]
	v_pk_mul_f32 v[32:33], v[32:33], v[128:129] op_sel_hi:[1,0]
	v_pk_fma_f32 v[32:33], v[32:33], v[154:155], v[186:187]
	v_pk_mul_f32 v[34:35], v[34:35], v[128:129] op_sel_hi:[1,0]
	v_pk_fma_f32 v[34:35], v[34:35], v[156:157], v[188:189]
	v_cvt_pk_bf16_f32 v32, v32, v33
	v_cvt_pk_bf16_f32 v33, v34, v35
	global_store_dwordx2 v[230:231], v[32:33], off offset:-2048
	v_pk_mul_f32 v[36:37], v[36:37], v[128:129] op_sel_hi:[1,0]
	v_pk_fma_f32 v[36:37], v[36:37], v[158:159], v[190:191]
	v_pk_mul_f32 v[38:39], v[38:39], v[128:129] op_sel_hi:[1,0]
	v_pk_fma_f32 v[38:39], v[38:39], v[160:161], v[192:193]
	v_cvt_pk_bf16_f32 v36, v36, v37
	v_cvt_pk_bf16_f32 v37, v38, v39
	global_store_dwordx2 v[230:231], v[36:37], off offset:-1536
	v_pk_mul_f32 v[40:41], v[40:41], v[128:129] op_sel_hi:[1,0]
	v_pk_fma_f32 v[40:41], v[40:41], v[162:163], v[194:195]
	v_pk_mul_f32 v[42:43], v[42:43], v[128:129] op_sel_hi:[1,0]
	v_pk_fma_f32 v[42:43], v[42:43], v[164:165], v[196:197]
	v_cvt_pk_bf16_f32 v40, v40, v41
	v_cvt_pk_bf16_f32 v41, v42, v43
	global_store_dwordx2 v[230:231], v[40:41], off offset:-1024
	v_pk_mul_f32 v[44:45], v[44:45], v[128:129] op_sel_hi:[1,0]
	v_pk_fma_f32 v[44:45], v[44:45], v[166:167], v[198:199]
	v_pk_mul_f32 v[46:47], v[46:47], v[128:129] op_sel_hi:[1,0]
	v_pk_fma_f32 v[46:47], v[46:47], v[168:169], v[200:201]
	v_cvt_pk_bf16_f32 v44, v44, v45
	v_cvt_pk_bf16_f32 v45, v46, v47
	global_store_dwordx2 v[230:231], v[44:45], off offset:-512
	v_pk_mul_f32 v[48:49], v[48:49], v[128:129] op_sel_hi:[1,0]
	v_pk_fma_f32 v[48:49], v[48:49], v[170:171], v[202:203]
	v_pk_mul_f32 v[50:51], v[50:51], v[128:129] op_sel_hi:[1,0]
	v_pk_fma_f32 v[50:51], v[50:51], v[172:173], v[204:205]
	v_cvt_pk_bf16_f32 v48, v48, v49
	v_cvt_pk_bf16_f32 v49, v50, v51
	global_store_dwordx2 v[230:231], v[48:49], off
	v_pk_mul_f32 v[52:53], v[52:53], v[128:129] op_sel_hi:[1,0]
	v_pk_fma_f32 v[52:53], v[52:53], v[174:175], v[206:207]
	v_pk_mul_f32 v[54:55], v[54:55], v[128:129] op_sel_hi:[1,0]
	v_pk_fma_f32 v[54:55], v[54:55], v[176:177], v[208:209]
	v_cvt_pk_bf16_f32 v52, v52, v53
	v_cvt_pk_bf16_f32 v53, v54, v55
	global_store_dwordx2 v[230:231], v[52:53], off offset:512
	v_pk_mul_f32 v[56:57], v[56:57], v[128:129] op_sel_hi:[1,0]
	v_pk_fma_f32 v[56:57], v[56:57], v[178:179], v[210:211]
	v_pk_mul_f32 v[58:59], v[58:59], v[128:129] op_sel_hi:[1,0]
	v_pk_fma_f32 v[58:59], v[58:59], v[180:181], v[212:213]
	v_cvt_pk_bf16_f32 v56, v56, v57
	v_cvt_pk_bf16_f32 v57, v58, v59
	global_store_dwordx2 v[230:231], v[56:57], off offset:1024
	v_pk_mul_f32 v[60:61], v[60:61], v[128:129] op_sel_hi:[1,0]
	v_pk_fma_f32 v[60:61], v[60:61], v[182:183], v[214:215]
	v_pk_mul_f32 v[62:63], v[62:63], v[128:129] op_sel_hi:[1,0]
	v_pk_fma_f32 v[62:63], v[62:63], v[184:185], v[216:217]
	v_cvt_pk_bf16_f32 v60, v60, v61
	v_cvt_pk_bf16_f32 v61, v62, v63
	global_store_dwordx2 v[230:231], v[60:61], off offset:1536
	s_add_i32 s6, s6, s82
	s_cmp_lt_i32 s6, 0x100
	s_cbranch_scc0 .Lnc_done
	s_cmp_lt_i32 s7, 0x100
	s_cselect_b32 s10, s7, s11
	s_lshl_b32 s8, s10, 13
	s_add_u32 s8, s8, 0x1000
	s_mov_b32 s9, 0
	v_lshl_add_u64 v[246:247], v[134:135], 0, s[8:9]
	global_load_dwordx4 v[32:35], v[246:247], off offset:-4096
	global_load_dwordx4 v[36:39], v[246:247], off offset:-3072
	global_load_dwordx4 v[40:43], v[246:247], off offset:-2048
	global_load_dwordx4 v[44:47], v[246:247], off offset:-1024
	global_load_dwordx4 v[48:51], v[246:247], off
	global_load_dwordx4 v[52:55], v[246:247], off offset:1024
	global_load_dwordx4 v[56:59], v[246:247], off offset:2048
	global_load_dwordx4 v[60:63], v[246:247], off offset:3072
	s_add_i32 s7, s7, s82
	s_waitcnt vmcnt(40)
	v_pk_mul_f32 v[218:219], v[64:65], v[64:65]
	v_pk_fma_f32 v[218:219], v[66:67], v[66:67], v[218:219]
	v_pk_mul_f32 v[220:221], v[68:69], v[68:69]
	v_pk_fma_f32 v[220:221], v[70:71], v[70:71], v[220:221]
	v_pk_mul_f32 v[222:223], v[72:73], v[72:73]
	v_pk_fma_f32 v[222:223], v[74:75], v[74:75], v[222:223]
	v_pk_mul_f32 v[224:225], v[76:77], v[76:77]
	v_pk_fma_f32 v[224:225], v[78:79], v[78:79], v[224:225]
	v_pk_fma_f32 v[218:219], v[80:81], v[80:81], v[218:219]
	v_pk_fma_f32 v[218:219], v[82:83], v[82:83], v[218:219]
	v_pk_fma_f32 v[220:221], v[84:85], v[84:85], v[220:221]
	v_pk_fma_f32 v[220:221], v[86:87], v[86:87], v[220:221]
	v_pk_fma_f32 v[222:223], v[88:89], v[88:89], v[222:223]
	v_pk_fma_f32 v[222:223], v[90:91], v[90:91], v[222:223]
	v_pk_fma_f32 v[224:225], v[92:93], v[92:93], v[224:225]
	v_pk_fma_f32 v[224:225], v[94:95], v[94:95], v[224:225]
	v_pk_add_f32 v[218:219], v[218:219], v[220:221]
	v_pk_add_f32 v[222:223], v[222:223], v[224:225]
	v_pk_add_f32 v[218:219], v[218:219], v[222:223]
	v_add_f32_e32 v128, v218, v219
	ds_bpermute_b32 v129, v140, v128
	s_waitcnt lgkmcnt(0)
	v_add_f32_e32 v128, v128, v129
	ds_bpermute_b32 v129, v141, v128
	s_waitcnt lgkmcnt(0)
	v_add_f32_e32 v128, v128, v129
	ds_bpermute_b32 v129, v142, v128
	s_waitcnt lgkmcnt(0)
	v_add_f32_e32 v128, v128, v129
	ds_bpermute_b32 v129, v150, v128
	s_waitcnt lgkmcnt(0)
	v_add_f32_e32 v128, v128, v129
	ds_bpermute_b32 v129, v151, v128
	s_waitcnt lgkmcnt(0)
	v_add_f32_e32 v128, v128, v129
	ds_bpermute_b32 v129, v152, v128
	s_waitcnt lgkmcnt(0)
; __device__ __forceinline__ unsigned cvt_pk_bf16(float lo, float hi) { unsigned r; asm volatile("v_cvt_pk_bf16_f32 %0, %1, %2" : "=v"(r) : "v"(lo), "v"(hi)); return r; }
; __device__ __forceinline__ void norm_rows(const float* src, int nrows, const float* gam, const float* sc, const float* sh, bf16_t* dst, int tid) {
;     ...
;     for (int q = 0; q < 4; ++q) { const f32x4* xr = (const f32x4*)(src + (size_t)rr[q] * DM) + lane;
; #pragma unroll
;       for (int j = 0; j < 8; ++j) v[q][j] = xr[64 * j]; }
; #pragma unroll
;     for (int q = 0; q < 4; ++q) { float s = 0.f;
; #pragma unroll
;       for (int j = 0; j < 8; ++j) s += v[q][j][0] * v[q][j][0] + v[q][j][1] * v[q][j][1] + v[q][j][2] * v[q][j][2] + v[q][j][3] * v[q][j][3];
;       ss[q] = rsqrtf(wave_sum(s) * (1.0f / DM) + 1e-6f); }
; #pragma unroll
;     for (int j = 0; j < 8; ++j) {
;       const int c = 4 * (lane + 64 * j);
;       const f32x4 mul = *(const f32x4*)(gam + c) * (1.0f + *(const f32x4*)(sc + c)); const f32x4 add = *(const f32x4*)(sh + c);
; #pragma unroll
;       for (int q = 0; q < 4; ++q) if (ok[q]) {
;         const f32x4 h = v[q][j] * ss[q] * mul + add; u32x2 w; w.x = cvt_pk_bf16(h[0], h[1]); w.y = cvt_pk_bf16(h[2], h[3]);
;         ((u32x2*)(dst + (size_t)rr[q] * DM) + lane)[64 * j] = w;
;       }
;     }
	v_add_f32_e32 v128, v128, v129
	v_fmamk_f32 v128, v128, 0x3a000000, v228
	v_mul_f32_e32 v129, 0x4b800000, v128
	v_cmp_gt_f32_e32 vcc, s67, v128
	s_nop 1
	v_cndmask_b32_e32 v128, v128, v129, vcc
	v_rsq_f32_e32 v128, v128
	s_nop 0
	v_mul_f32_e32 v129, 0x45800000, v128
	v_cndmask_b32_e32 v128, v128, v129, vcc
	s_lshl_b32 s8, s6, 12
	s_add_u32 s8, s8, 0x800
	s_mov_b32 s9, 0
	v_lshl_add_u64 v[230:231], v[136:137], 0, s[8:9]
	v_pk_mul_f32 v[64:65], v[64:65], v[128:129] op_sel_hi:[1,0]
	v_pk_fma_f32 v[64:65], v[64:65], v[154:155], v[186:187]
	v_pk_mul_f32 v[66:67], v[66:67], v[128:129] op_sel_hi:[1,0]
	v_pk_fma_f32 v[66:67], v[66:67], v[156:157], v[188:189]
	v_cvt_pk_bf16_f32 v64, v64, v65
	v_cvt_pk_bf16_f32 v65, v66, v67
	global_store_dwordx2 v[230:231], v[64:65], off offset:-2048
	v_pk_mul_f32 v[68:69], v[68:69], v[128:129] op_sel_hi:[1,0]
	v_pk_fma_f32 v[68:69], v[68:69], v[158:159], v[190:191]
	v_pk_mul_f32 v[70:71], v[70:71], v[128:129] op_sel_hi:[1,0]
	v_pk_fma_f32 v[70:71], v[70:71], v[160:161], v[192:193]
	v_cvt_pk_bf16_f32 v68, v68, v69
	v_cvt_pk_bf16_f32 v69, v70, v71
	global_store_dwordx2 v[230:231], v[68:69], off offset:-1536
	v_pk_mul_f32 v[72:73], v[72:73], v[128:129] op_sel_hi:[1,0]
	v_pk_fma_f32 v[72:73], v[72:73], v[162:163], v[194:195]
	v_pk_mul_f32 v[74:75], v[74:75], v[128:129] op_sel_hi:[1,0]
	v_pk_fma_f32 v[74:75], v[74:75], v[164:165], v[196:197]
	v_cvt_pk_bf16_f32 v72, v72, v73
	v_cvt_pk_bf16_f32 v73, v74, v75
	global_store_dwordx2 v[230:231], v[72:73], off offset:-1024
	v_pk_mul_f32 v[76:77], v[76:77], v[128:129] op_sel_hi:[1,0]
	v_pk_fma_f32 v[76:77], v[76:77], v[166:167], v[198:199]
	v_pk_mul_f32 v[78:79], v[78:79], v[128:129] op_sel_hi:[1,0]
	v_pk_fma_f32 v[78:79], v[78:79], v[168:169], v[200:201]
	v_cvt_pk_bf16_f32 v76, v76, v77
	v_cvt_pk_bf16_f32 v77, v78, v79
	global_store_dwordx2 v[230:231], v[76:77], off offset:-512
	v_pk_mul_f32 v[80:81], v[80:81], v[128:129] op_sel_hi:[1,0]
	v_pk_fma_f32 v[80:81], v[80:81], v[170:171], v[202:203]
	v_pk_mul_f32 v[82:83], v[82:83], v[128:129] op_sel_hi:[1,0]
	v_pk_fma_f32 v[82:83], v[82:83], v[172:173], v[204:205]
	v_cvt_pk_bf16_f32 v80, v80, v81
	v_cvt_pk_bf16_f32 v81, v82, v83
	global_store_dwordx2 v[230:231], v[80:81], off
	v_pk_mul_f32 v[84:85], v[84:85], v[128:129] op_sel_hi:[1,0]
	v_pk_fma_f32 v[84:85], v[84:85], v[174:175], v[206:207]
	v_pk_mul_f32 v[86:87], v[86:87], v[128:129] op_sel_hi:[1,0]
	v_pk_fma_f32 v[86:87], v[86:87], v[176:177], v[208:209]
	v_cvt_pk_bf16_f32 v84, v84, v85
	v_cvt_pk_bf16_f32 v85, v86, v87
	global_store_dwordx2 v[230:231], v[84:85], off offset:512
	v_pk_mul_f32 v[88:89], v[88:89], v[128:129] op_sel_hi:[1,0]
	v_pk_fma_f32 v[88:89], v[88:89], v[178:179], v[210:211]
	v_pk_mul_f32 v[90:91], v[90:91], v[128:129] op_sel_hi:[1,0]
	v_pk_fma_f32 v[90:91], v[90:91], v[180:181], v[212:213]
	v_cvt_pk_bf16_f32 v88, v88, v89
	v_cvt_pk_bf16_f32 v89, v90, v91
	global_store_dwordx2 v[230:231], v[88:89], off offset:1024
	v_pk_mul_f32 v[92:93], v[92:93], v[128:129] op_sel_hi:[1,0]
	v_pk_fma_f32 v[92:93], v[92:93], v[182:183], v[214:215]
	v_pk_mul_f32 v[94:95], v[94:95], v[128:129] op_sel_hi:[1,0]
	v_pk_fma_f32 v[94:95], v[94:95], v[184:185], v[216:217]
	v_cvt_pk_bf16_f32 v92, v92, v93
	v_cvt_pk_bf16_f32 v93, v94, v95
	global_store_dwordx2 v[230:231], v[92:93], off offset:1536
	s_add_i32 s6, s6, s82
	s_cmp_lt_i32 s6, 0x100
	s_cbranch_scc0 .Lnc_done
.Lnc_loop:
	s_cmp_lt_i32 s7, 0x100
	s_cselect_b32 s10, s7, s11
	s_lshl_b32 s8, s10, 13
	s_add_u32 s8, s8, 0x1000
	s_mov_b32 s9, 0
	v_lshl_add_u64 v[248:249], v[134:135], 0, s[8:9]
	global_load_dwordx4 v[64:67], v[248:249], off offset:-4096
	global_load_dwordx4 v[68:71], v[248:249], off offset:-3072
	global_load_dwordx4 v[72:75], v[248:249], off offset:-2048
	global_load_dwordx4 v[76:79], v[248:249], off offset:-1024
	global_load_dwordx4 v[80:83], v[248:249], off
	global_load_dwordx4 v[84:87], v[248:249], off offset:1024
	global_load_dwordx4 v[88:91], v[248:249], off offset:2048
	global_load_dwordx4 v[92:95], v[248:249], off offset:3072
	s_add_i32 s7, s7, s82
	s_waitcnt vmcnt(48)
	v_pk_mul_f32 v[218:219], v[96:97], v[96:97]
	v_pk_fma_f32 v[218:219], v[98:99], v[98:99], v[218:219]
	v_pk_mul_f32 v[220:221], v[100:101], v[100:101]
	v_pk_fma_f32 v[220:221], v[102:103], v[102:103], v[220:221]
	v_pk_mul_f32 v[222:223], v[104:105], v[104:105]
	v_pk_fma_f32 v[222:223], v[106:107], v[106:107], v[222:223]
	v_pk_mul_f32 v[224:225], v[108:109], v[108:109]
	v_pk_fma_f32 v[224:225], v[110:111], v[110:111], v[224:225]
	v_pk_fma_f32 v[218:219], v[112:113], v[112:113], v[218:219]
	v_pk_fma_f32 v[218:219], v[114:115], v[114:115], v[218:219]
	v_pk_fma_f32 v[220:221], v[116:117], v[116:117], v[220:221]
	v_pk_fma_f32 v[220:221], v[118:119], v[118:119], v[220:221]
	v_pk_fma_f32 v[222:223], v[120:121], v[120:121], v[222:223]
	v_pk_fma_f32 v[222:223], v[122:123], v[122:123], v[222:223]
	v_pk_fma_f32 v[224:225], v[124:125], v[124:125], v[224:225]
	v_pk_fma_f32 v[224:225], v[126:127], v[126:127], v[224:225]
	v_pk_add_f32 v[218:219], v[218:219], v[220:221]
	v_pk_add_f32 v[222:223], v[222:223], v[224:225]
	v_pk_add_f32 v[218:219], v[218:219], v[222:223]
	v_add_f32_e32 v128, v218, v219
	ds_bpermute_b32 v129, v140, v128
	s_waitcnt lgkmcnt(0)
	v_add_f32_e32 v128, v128, v129
	ds_bpermute_b32 v129, v141, v128
	s_waitcnt lgkmcnt(0)
	v_add_f32_e32 v128, v128, v129
	ds_bpermute_b32 v129, v142, v128
	s_waitcnt lgkmcnt(0)
	v_add_f32_e32 v128, v128, v129
	ds_bpermute_b32 v129, v150, v128
	s_waitcnt lgkmcnt(0)
	v_add_f32_e32 v128, v128, v129
	ds_bpermute_b32 v129, v151, v128
	s_waitcnt lgkmcnt(0)
	v_add_f32_e32 v128, v128, v129
	ds_bpermute_b32 v129, v152, v128
	s_waitcnt lgkmcnt(0)
; __device__ __forceinline__ unsigned cvt_pk_bf16(float lo, float hi) { unsigned r; asm volatile("v_cvt_pk_bf16_f32 %0, %1, %2" : "=v"(r) : "v"(lo), "v"(hi)); return r; }
; __device__ __forceinline__ void norm_rows(const float* src, int nrows, const float* gam, const float* sc, const float* sh, bf16_t* dst, int tid) {
;     ...
;     for (int q = 0; q < 4; ++q) { const f32x4* xr = (const f32x4*)(src + (size_t)rr[q] * DM) + lane;
; #pragma unroll
;       for (int j = 0; j < 8; ++j) v[q][j] = xr[64 * j]; }
; #pragma unroll
;     for (int q = 0; q < 4; ++q) { float s = 0.f;
; #pragma unroll
;       for (int j = 0; j < 8; ++j) s += v[q][j][0] * v[q][j][0] + v[q][j][1] * v[q][j][1] + v[q][j][2] * v[q][j][2] + v[q][j][3] * v[q][j][3];
;       ss[q] = rsqrtf(wave_sum(s) * (1.0f / DM) + 1e-6f); }
; #pragma unroll
;     for (int j = 0; j < 8; ++j) {
;       const int c = 4 * (lane + 64 * j);
;       const f32x4 mul = *(const f32x4*)(gam + c) * (1.0f + *(const f32x4*)(sc + c)); const f32x4 add = *(const f32x4*)(sh + c);
; #pragma unroll
;       for (int q = 0; q < 4; ++q) if (ok[q]) {
;         const f32x4 h = v[q][j] * ss[q] * mul + add; u32x2 w; w.x = cvt_pk_bf16(h[0], h[1]); w.y = cvt_pk_bf16(h[2], h[3]);
;         ((u32x2*)(dst + (size_t)rr[q] * DM) + lane)[64 * j] = w;
;       }
;     }
	v_add_f32_e32 v128, v128, v129
	v_fmamk_f32 v128, v128, 0x3a000000, v228
	v_mul_f32_e32 v129, 0x4b800000, v128
	v_cmp_gt_f32_e32 vcc, s67, v128
	s_nop 1
	v_cndmask_b32_e32 v128, v128, v129, vcc
	v_rsq_f32_e32 v128, v128
	s_nop 0
	v_mul_f32_e32 v129, 0x45800000, v128
	v_cndmask_b32_e32 v128, v128, v129, vcc
	s_lshl_b32 s8, s6, 12
	s_add_u32 s8, s8, 0x800
	s_mov_b32 s9, 0
	v_lshl_add_u64 v[230:231], v[136:137], 0, s[8:9]
	v_pk_mul_f32 v[96:97], v[96:97], v[128:129] op_sel_hi:[1,0]
	v_pk_fma_f32 v[96:97], v[96:97], v[154:155], v[186:187]
	v_pk_mul_f32 v[98:99], v[98:99], v[128:129] op_sel_hi:[1,0]
	v_pk_fma_f32 v[98:99], v[98:99], v[156:157], v[188:189]
	v_cvt_pk_bf16_f32 v96, v96, v97
	v_cvt_pk_bf16_f32 v97, v98, v99
	global_store_dwordx2 v[230:231], v[96:97], off offset:-2048
	v_pk_mul_f32 v[100:101], v[100:101], v[128:129] op_sel_hi:[1,0]
	v_pk_fma_f32 v[100:101], v[100:101], v[158:159], v[190:191]
	v_pk_mul_f32 v[102:103], v[102:103], v[128:129] op_sel_hi:[1,0]
	v_pk_fma_f32 v[102:103], v[102:103], v[160:161], v[192:193]
	v_cvt_pk_bf16_f32 v100, v100, v101
	v_cvt_pk_bf16_f32 v101, v102, v103
	global_store_dwordx2 v[230:231], v[100:101], off offset:-1536
	v_pk_mul_f32 v[104:105], v[104:105], v[128:129] op_sel_hi:[1,0]
	v_pk_fma_f32 v[104:105], v[104:105], v[162:163], v[194:195]
	v_pk_mul_f32 v[106:107], v[106:107], v[128:129] op_sel_hi:[1,0]
	v_pk_fma_f32 v[106:107], v[106:107], v[164:165], v[196:197]
	v_cvt_pk_bf16_f32 v104, v104, v105
	v_cvt_pk_bf16_f32 v105, v106, v107
	global_store_dwordx2 v[230:231], v[104:105], off offset:-1024
	v_pk_mul_f32 v[108:109], v[108:109], v[128:129] op_sel_hi:[1,0]
	v_pk_fma_f32 v[108:109], v[108:109], v[166:167], v[198:199]
	v_pk_mul_f32 v[110:111], v[110:111], v[128:129] op_sel_hi:[1,0]
	v_pk_fma_f32 v[110:111], v[110:111], v[168:169], v[200:201]
	v_cvt_pk_bf16_f32 v108, v108, v109
	v_cvt_pk_bf16_f32 v109, v110, v111
	global_store_dwordx2 v[230:231], v[108:109], off offset:-512
	v_pk_mul_f32 v[112:113], v[112:113], v[128:129] op_sel_hi:[1,0]
	v_pk_fma_f32 v[112:113], v[112:113], v[170:171], v[202:203]
	v_pk_mul_f32 v[114:115], v[114:115], v[128:129] op_sel_hi:[1,0]
	v_pk_fma_f32 v[114:115], v[114:115], v[172:173], v[204:205]
	v_cvt_pk_bf16_f32 v112, v112, v113
	v_cvt_pk_bf16_f32 v113, v114, v115
	global_store_dwordx2 v[230:231], v[112:113], off
	v_pk_mul_f32 v[116:117], v[116:117], v[128:129] op_sel_hi:[1,0]
	v_pk_fma_f32 v[116:117], v[116:117], v[174:175], v[206:207]
	v_pk_mul_f32 v[118:119], v[118:119], v[128:129] op_sel_hi:[1,0]
	v_pk_fma_f32 v[118:119], v[118:119], v[176:177], v[208:209]
	v_cvt_pk_bf16_f32 v116, v116, v117
	v_cvt_pk_bf16_f32 v117, v118, v119
	global_store_dwordx2 v[230:231], v[116:117], off offset:512
	v_pk_mul_f32 v[120:121], v[120:121], v[128:129] op_sel_hi:[1,0]
	v_pk_fma_f32 v[120:121], v[120:121], v[178:179], v[210:211]
	v_pk_mul_f32 v[122:123], v[122:123], v[128:129] op_sel_hi:[1,0]
	v_pk_fma_f32 v[122:123], v[122:123], v[180:181], v[212:213]
	v_cvt_pk_bf16_f32 v120, v120, v121
	v_cvt_pk_bf16_f32 v121, v122, v123
	global_store_dwordx2 v[230:231], v[120:121], off offset:1024
	v_pk_mul_f32 v[124:125], v[124:125], v[128:129] op_sel_hi:[1,0]
	v_pk_fma_f32 v[124:125], v[124:125], v[182:183], v[214:215]
	v_pk_mul_f32 v[126:127], v[126:127], v[128:129] op_sel_hi:[1,0]
	v_pk_fma_f32 v[126:127], v[126:127], v[184:185], v[216:217]
	v_cvt_pk_bf16_f32 v124, v124, v125
	v_cvt_pk_bf16_f32 v125, v126, v127
	global_store_dwordx2 v[230:231], v[124:125], off offset:1536
	s_add_i32 s6, s6, s82
	s_cmp_lt_i32 s6, 0x100
	s_cbranch_scc0 .Lnc_done
	s_cmp_lt_i32 s7, 0x100
	s_cselect_b32 s10, s7, s11
	s_lshl_b32 s8, s10, 13
	s_add_u32 s8, s8, 0x1000
	s_mov_b32 s9, 0
	v_lshl_add_u64 v[250:251], v[134:135], 0, s[8:9]
	global_load_dwordx4 v[96:99], v[250:251], off offset:-4096
	global_load_dwordx4 v[100:103], v[250:251], off offset:-3072
	global_load_dwordx4 v[104:107], v[250:251], off offset:-2048
	global_load_dwordx4 v[108:111], v[250:251], off offset:-1024
	global_load_dwordx4 v[112:115], v[250:251], off
	global_load_dwordx4 v[116:119], v[250:251], off offset:1024
	global_load_dwordx4 v[120:123], v[250:251], off offset:2048
	global_load_dwordx4 v[124:127], v[250:251], off offset:3072
	s_add_i32 s7, s7, s82
	s_waitcnt vmcnt(48)
	v_pk_mul_f32 v[218:219], v[0:1], v[0:1]
	v_pk_fma_f32 v[218:219], v[2:3], v[2:3], v[218:219]
	v_pk_mul_f32 v[220:221], v[4:5], v[4:5]
	v_pk_fma_f32 v[220:221], v[6:7], v[6:7], v[220:221]
	v_pk_mul_f32 v[222:223], v[8:9], v[8:9]
	v_pk_fma_f32 v[222:223], v[10:11], v[10:11], v[222:223]
	v_pk_mul_f32 v[224:225], v[12:13], v[12:13]
	v_pk_fma_f32 v[224:225], v[14:15], v[14:15], v[224:225]
	v_pk_fma_f32 v[218:219], v[16:17], v[16:17], v[218:219]
	v_pk_fma_f32 v[218:219], v[18:19], v[18:19], v[218:219]
	v_pk_fma_f32 v[220:221], v[20:21], v[20:21], v[220:221]
	v_pk_fma_f32 v[220:221], v[22:23], v[22:23], v[220:221]
	v_pk_fma_f32 v[222:223], v[24:25], v[24:25], v[222:223]
	v_pk_fma_f32 v[222:223], v[26:27], v[26:27], v[222:223]
	v_pk_fma_f32 v[224:225], v[28:29], v[28:29], v[224:225]
	v_pk_fma_f32 v[224:225], v[30:31], v[30:31], v[224:225]
	v_pk_add_f32 v[218:219], v[218:219], v[220:221]
	v_pk_add_f32 v[222:223], v[222:223], v[224:225]
	v_pk_add_f32 v[218:219], v[218:219], v[222:223]
	v_add_f32_e32 v128, v218, v219
	ds_bpermute_b32 v129, v140, v128
	s_waitcnt lgkmcnt(0)
	v_add_f32_e32 v128, v128, v129
	ds_bpermute_b32 v129, v141, v128
	s_waitcnt lgkmcnt(0)
	v_add_f32_e32 v128, v128, v129
	ds_bpermute_b32 v129, v142, v128
	s_waitcnt lgkmcnt(0)
	v_add_f32_e32 v128, v128, v129
	ds_bpermute_b32 v129, v150, v128
	s_waitcnt lgkmcnt(0)
	v_add_f32_e32 v128, v128, v129
	ds_bpermute_b32 v129, v151, v128
	s_waitcnt lgkmcnt(0)
; __device__ __forceinline__ unsigned cvt_pk_bf16(float lo, float hi) { unsigned r; asm volatile("v_cvt_pk_bf16_f32 %0, %1, %2" : "=v"(r) : "v"(lo), "v"(hi)); return r; }
; __device__ __forceinline__ void norm_rows(const float* src, int nrows, const float* gam, const float* sc, const float* sh, bf16_t* dst, int tid) {
;     ...
;     for (int q = 0; q < 4; ++q) { const f32x4* xr = (const f32x4*)(src + (size_t)rr[q] * DM) + lane;
; #pragma unroll
;       for (int j = 0; j < 8; ++j) v[q][j] = xr[64 * j]; }
; #pragma unroll
;     for (int q = 0; q < 4; ++q) { float s = 0.f;
; #pragma unroll
;       for (int j = 0; j < 8; ++j) s += v[q][j][0] * v[q][j][0] + v[q][j][1] * v[q][j][1] + v[q][j][2] * v[q][j][2] + v[q][j][3] * v[q][j][3];
;       ss[q] = rsqrtf(wave_sum(s) * (1.0f / DM) + 1e-6f); }
; #pragma unroll
;     for (int j = 0; j < 8; ++j) {
;       const int c = 4 * (lane + 64 * j);
;       const f32x4 mul = *(const f32x4*)(gam + c) * (1.0f + *(const f32x4*)(sc + c)); const f32x4 add = *(const f32x4*)(sh + c);
; #pragma unroll
;       for (int q = 0; q < 4; ++q) if (ok[q]) {
;         const f32x4 h = v[q][j] * ss[q] * mul + add; u32x2 w; w.x = cvt_pk_bf16(h[0], h[1]); w.y = cvt_pk_bf16(h[2], h[3]);
;         ((u32x2*)(dst + (size_t)rr[q] * DM) + lane)[64 * j] = w;
;       }
;     }
	v_add_f32_e32 v128, v128, v129
	ds_bpermute_b32 v129, v152, v128
	s_waitcnt lgkmcnt(0)
	v_add_f32_e32 v128, v128, v129
	v_fmamk_f32 v128, v128, 0x3a000000, v228
	v_mul_f32_e32 v129, 0x4b800000, v128
	v_cmp_gt_f32_e32 vcc, s67, v128
	s_nop 1
	v_cndmask_b32_e32 v128, v128, v129, vcc
	v_rsq_f32_e32 v128, v128
	s_nop 0
	v_mul_f32_e32 v129, 0x45800000, v128
	v_cndmask_b32_e32 v128, v128, v129, vcc
	s_lshl_b32 s8, s6, 12
	s_add_u32 s8, s8, 0x800
	s_mov_b32 s9, 0
	v_lshl_add_u64 v[230:231], v[136:137], 0, s[8:9]
	v_pk_mul_f32 v[0:1], v[0:1], v[128:129] op_sel_hi:[1,0]
	v_pk_fma_f32 v[0:1], v[0:1], v[154:155], v[186:187]
	v_pk_mul_f32 v[2:3], v[2:3], v[128:129] op_sel_hi:[1,0]
	v_pk_fma_f32 v[2:3], v[2:3], v[156:157], v[188:189]
	v_cvt_pk_bf16_f32 v0, v0, v1
	v_cvt_pk_bf16_f32 v1, v2, v3
	global_store_dwordx2 v[230:231], v[0:1], off offset:-2048
	v_pk_mul_f32 v[4:5], v[4:5], v[128:129] op_sel_hi:[1,0]
	v_pk_fma_f32 v[4:5], v[4:5], v[158:159], v[190:191]
	v_pk_mul_f32 v[6:7], v[6:7], v[128:129] op_sel_hi:[1,0]
	v_pk_fma_f32 v[6:7], v[6:7], v[160:161], v[192:193]
	v_cvt_pk_bf16_f32 v4, v4, v5
	v_cvt_pk_bf16_f32 v5, v6, v7
	global_store_dwordx2 v[230:231], v[4:5], off offset:-1536
	v_pk_mul_f32 v[8:9], v[8:9], v[128:129] op_sel_hi:[1,0]
	v_pk_fma_f32 v[8:9], v[8:9], v[162:163], v[194:195]
	v_pk_mul_f32 v[10:11], v[10:11], v[128:129] op_sel_hi:[1,0]
	v_pk_fma_f32 v[10:11], v[10:11], v[164:165], v[196:197]
	v_cvt_pk_bf16_f32 v8, v8, v9
	v_cvt_pk_bf16_f32 v9, v10, v11
	global_store_dwordx2 v[230:231], v[8:9], off offset:-1024
	v_pk_mul_f32 v[12:13], v[12:13], v[128:129] op_sel_hi:[1,0]
	v_pk_fma_f32 v[12:13], v[12:13], v[166:167], v[198:199]
	v_pk_mul_f32 v[14:15], v[14:15], v[128:129] op_sel_hi:[1,0]
	v_pk_fma_f32 v[14:15], v[14:15], v[168:169], v[200:201]
	v_cvt_pk_bf16_f32 v12, v12, v13
	v_cvt_pk_bf16_f32 v13, v14, v15
	global_store_dwordx2 v[230:231], v[12:13], off offset:-512
	v_pk_mul_f32 v[16:17], v[16:17], v[128:129] op_sel_hi:[1,0]
	v_pk_fma_f32 v[16:17], v[16:17], v[170:171], v[202:203]
	v_pk_mul_f32 v[18:19], v[18:19], v[128:129] op_sel_hi:[1,0]
	v_pk_fma_f32 v[18:19], v[18:19], v[172:173], v[204:205]
	v_cvt_pk_bf16_f32 v16, v16, v17
	v_cvt_pk_bf16_f32 v17, v18, v19
	global_store_dwordx2 v[230:231], v[16:17], off
	v_pk_mul_f32 v[20:21], v[20:21], v[128:129] op_sel_hi:[1,0]
	v_pk_fma_f32 v[20:21], v[20:21], v[174:175], v[206:207]
	v_pk_mul_f32 v[22:23], v[22:23], v[128:129] op_sel_hi:[1,0]
	v_pk_fma_f32 v[22:23], v[22:23], v[176:177], v[208:209]
	v_cvt_pk_bf16_f32 v20, v20, v21
	v_cvt_pk_bf16_f32 v21, v22, v23
	global_store_dwordx2 v[230:231], v[20:21], off offset:512
	v_pk_mul_f32 v[24:25], v[24:25], v[128:129] op_sel_hi:[1,0]
	v_pk_fma_f32 v[24:25], v[24:25], v[178:179], v[210:211]
	v_pk_mul_f32 v[26:27], v[26:27], v[128:129] op_sel_hi:[1,0]
	v_pk_fma_f32 v[26:27], v[26:27], v[180:181], v[212:213]
	v_cvt_pk_bf16_f32 v24, v24, v25
	v_cvt_pk_bf16_f32 v25, v26, v27
	global_store_dwordx2 v[230:231], v[24:25], off offset:1024
	v_pk_mul_f32 v[28:29], v[28:29], v[128:129] op_sel_hi:[1,0]
	v_pk_fma_f32 v[28:29], v[28:29], v[182:183], v[214:215]
	v_pk_mul_f32 v[30:31], v[30:31], v[128:129] op_sel_hi:[1,0]
	v_pk_fma_f32 v[30:31], v[30:31], v[184:185], v[216:217]
	v_cvt_pk_bf16_f32 v28, v28, v29
	v_cvt_pk_bf16_f32 v29, v30, v31
	global_store_dwordx2 v[230:231], v[28:29], off offset:1536
	s_add_i32 s6, s6, s82
	s_cmp_lt_i32 s6, 0x100
	s_cbranch_scc0 .Lnc_done
	s_cmp_lt_i32 s7, 0x100
	s_cselect_b32 s10, s7, s11
	s_lshl_b32 s8, s10, 13
	s_add_u32 s8, s8, 0x1000
	s_mov_b32 s9, 0
	v_lshl_add_u64 v[244:245], v[134:135], 0, s[8:9]
	global_load_dwordx4 v[0:3], v[244:245], off offset:-4096
	global_load_dwordx4 v[4:7], v[244:245], off offset:-3072
	global_load_dwordx4 v[8:11], v[244:245], off offset:-2048
	global_load_dwordx4 v[12:15], v[244:245], off offset:-1024
	global_load_dwordx4 v[16:19], v[244:245], off
	global_load_dwordx4 v[20:23], v[244:245], off offset:1024
	global_load_dwordx4 v[24:27], v[244:245], off offset:2048
	global_load_dwordx4 v[28:31], v[244:245], off offset:3072
	s_add_i32 s7, s7, s82
	s_waitcnt vmcnt(48)
	v_pk_mul_f32 v[218:219], v[32:33], v[32:33]
	v_pk_fma_f32 v[218:219], v[34:35], v[34:35], v[218:219]
	v_pk_mul_f32 v[220:221], v[36:37], v[36:37]
	v_pk_fma_f32 v[220:221], v[38:39], v[38:39], v[220:221]
	v_pk_mul_f32 v[222:223], v[40:41], v[40:41]
	v_pk_fma_f32 v[222:223], v[42:43], v[42:43], v[222:223]
	v_pk_mul_f32 v[224:225], v[44:45], v[44:45]
	v_pk_fma_f32 v[224:225], v[46:47], v[46:47], v[224:225]
	v_pk_fma_f32 v[218:219], v[48:49], v[48:49], v[218:219]
	v_pk_fma_f32 v[218:219], v[50:51], v[50:51], v[218:219]
	v_pk_fma_f32 v[220:221], v[52:53], v[52:53], v[220:221]
	v_pk_fma_f32 v[220:221], v[54:55], v[54:55], v[220:221]
	v_pk_fma_f32 v[222:223], v[56:57], v[56:57], v[222:223]
	v_pk_fma_f32 v[222:223], v[58:59], v[58:59], v[222:223]
	v_pk_fma_f32 v[224:225], v[60:61], v[60:61], v[224:225]
	v_pk_fma_f32 v[224:225], v[62:63], v[62:63], v[224:225]
	v_pk_add_f32 v[218:219], v[218:219], v[220:221]
	v_pk_add_f32 v[222:223], v[222:223], v[224:225]
	v_pk_add_f32 v[218:219], v[218:219], v[222:223]
	v_add_f32_e32 v128, v218, v219
	ds_bpermute_b32 v129, v140, v128
	s_waitcnt lgkmcnt(0)
	v_add_f32_e32 v128, v128, v129
	ds_bpermute_b32 v129, v141, v128
	s_waitcnt lgkmcnt(0)
	v_add_f32_e32 v128, v128, v129
	ds_bpermute_b32 v129, v142, v128
	s_waitcnt lgkmcnt(0)
	v_add_f32_e32 v128, v128, v129
	ds_bpermute_b32 v129, v150, v128
	s_waitcnt lgkmcnt(0)
	v_add_f32_e32 v128, v128, v129
	ds_bpermute_b32 v129, v151, v128
	s_waitcnt lgkmcnt(0)
	v_add_f32_e32 v128, v128, v129
	ds_bpermute_b32 v129, v152, v128
	s_waitcnt lgkmcnt(0)
; __device__ __forceinline__ unsigned cvt_pk_bf16(float lo, float hi) { unsigned r; asm volatile("v_cvt_pk_bf16_f32 %0, %1, %2" : "=v"(r) : "v"(lo), "v"(hi)); return r; }
; __device__ __forceinline__ void norm_rows(const float* src, int nrows, const float* gam, const float* sc, const float* sh, bf16_t* dst, int tid) {
;     ...
;       ss[q] = rsqrtf(wave_sum(s) * (1.0f / DM) + 1e-6f); }
; #pragma unroll
;     for (int j = 0; j < 8; ++j) {
;       const int c = 4 * (lane + 64 * j);
;       const f32x4 mul = *(const f32x4*)(gam + c) * (1.0f + *(const f32x4*)(sc + c)); const f32x4 add = *(const f32x4*)(sh + c);
; #pragma unroll
;       for (int q = 0; q < 4; ++q) if (ok[q]) {
;         const f32x4 h = v[q][j] * ss[q] * mul + add; u32x2 w; w.x = cvt_pk_bf16(h[0], h[1]); w.y = cvt_pk_bf16(h[2], h[3]);
;         ((u32x2*)(dst + (size_t)rr[q] * DM) + lane)[64 * j] = w;
;       }
;     }
	v_add_f32_e32 v128, v128, v129
	v_fmamk_f32 v128, v128, 0x3a000000, v228
	v_mul_f32_e32 v129, 0x4b800000, v128
	v_cmp_gt_f32_e32 vcc, s67, v128
	s_nop 1
	v_cndmask_b32_e32 v128, v128, v129, vcc
	v_rsq_f32_e32 v128, v128
	s_nop 0
	v_mul_f32_e32 v129, 0x45800000, v128
	v_cndmask_b32_e32 v128, v128, v129, vcc
	s_lshl_b32 s8, s6, 12
	s_add_u32 s8, s8, 0x800
	s_mov_b32 s9, 0
	v_lshl_add_u64 v[230:231], v[136:137], 0, s[8:9]
	v_pk_mul_f32 v[32:33], v[32:33], v[128:129] op_sel_hi:[1,0]
	v_pk_fma_f32 v[32:33], v[32:33], v[154:155], v[186:187]
	v_pk_mul_f32 v[34:35], v[34:35], v[128:129] op_sel_hi:[1,0]
	v_pk_fma_f32 v[34:35], v[34:35], v[156:157], v[188:189]
	v_cvt_pk_bf16_f32 v32, v32, v33
	v_cvt_pk_bf16_f32 v33, v34, v35
	global_store_dwordx2 v[230:231], v[32:33], off offset:-2048
	v_pk_mul_f32 v[36:37], v[36:37], v[128:129] op_sel_hi:[1,0]
	v_pk_fma_f32 v[36:37], v[36:37], v[158:159], v[190:191]
	v_pk_mul_f32 v[38:39], v[38:39], v[128:129] op_sel_hi:[1,0]
	v_pk_fma_f32 v[38:39], v[38:39], v[160:161], v[192:193]
	v_cvt_pk_bf16_f32 v36, v36, v37
	v_cvt_pk_bf16_f32 v37, v38, v39
	global_store_dwordx2 v[230:231], v[36:37], off offset:-1536
	v_pk_mul_f32 v[40:41], v[40:41], v[128:129] op_sel_hi:[1,0]
	v_pk_fma_f32 v[40:41], v[40:41], v[162:163], v[194:195]
	v_pk_mul_f32 v[42:43], v[42:43], v[128:129] op_sel_hi:[1,0]
	v_pk_fma_f32 v[42:43], v[42:43], v[164:165], v[196:197]
	v_cvt_pk_bf16_f32 v40, v40, v41
	v_cvt_pk_bf16_f32 v41, v42, v43
	global_store_dwordx2 v[230:231], v[40:41], off offset:-1024
	v_pk_mul_f32 v[44:45], v[44:45], v[128:129] op_sel_hi:[1,0]
	v_pk_fma_f32 v[44:45], v[44:45], v[166:167], v[198:199]
	v_pk_mul_f32 v[46:47], v[46:47], v[128:129] op_sel_hi:[1,0]
	v_pk_fma_f32 v[46:47], v[46:47], v[168:169], v[200:201]
	v_cvt_pk_bf16_f32 v44, v44, v45
	v_cvt_pk_bf16_f32 v45, v46, v47
	global_store_dwordx2 v[230:231], v[44:45], off offset:-512
	v_pk_mul_f32 v[48:49], v[48:49], v[128:129] op_sel_hi:[1,0]
	v_pk_fma_f32 v[48:49], v[48:49], v[170:171], v[202:203]
	v_pk_mul_f32 v[50:51], v[50:51], v[128:129] op_sel_hi:[1,0]
	v_pk_fma_f32 v[50:51], v[50:51], v[172:173], v[204:205]
	v_cvt_pk_bf16_f32 v48, v48, v49
	v_cvt_pk_bf16_f32 v49, v50, v51
	global_store_dwordx2 v[230:231], v[48:49], off
	v_pk_mul_f32 v[52:53], v[52:53], v[128:129] op_sel_hi:[1,0]
	v_pk_fma_f32 v[52:53], v[52:53], v[174:175], v[206:207]
	v_pk_mul_f32 v[54:55], v[54:55], v[128:129] op_sel_hi:[1,0]
	v_pk_fma_f32 v[54:55], v[54:55], v[176:177], v[208:209]
	v_cvt_pk_bf16_f32 v52, v52, v53
	v_cvt_pk_bf16_f32 v53, v54, v55
	global_store_dwordx2 v[230:231], v[52:53], off offset:512
	v_pk_mul_f32 v[56:57], v[56:57], v[128:129] op_sel_hi:[1,0]
	v_pk_fma_f32 v[56:57], v[56:57], v[178:179], v[210:211]
	v_pk_mul_f32 v[58:59], v[58:59], v[128:129] op_sel_hi:[1,0]
	v_pk_fma_f32 v[58:59], v[58:59], v[180:181], v[212:213]
	v_cvt_pk_bf16_f32 v56, v56, v57
	v_cvt_pk_bf16_f32 v57, v58, v59
	global_store_dwordx2 v[230:231], v[56:57], off offset:1024
	v_pk_mul_f32 v[60:61], v[60:61], v[128:129] op_sel_hi:[1,0]
	v_pk_fma_f32 v[60:61], v[60:61], v[182:183], v[214:215]
	v_pk_mul_f32 v[62:63], v[62:63], v[128:129] op_sel_hi:[1,0]
	v_pk_fma_f32 v[62:63], v[62:63], v[184:185], v[216:217]
	v_cvt_pk_bf16_f32 v60, v60, v61
	v_cvt_pk_bf16_f32 v61, v62, v63
	global_store_dwordx2 v[230:231], v[60:61], off offset:1536
	s_add_i32 s6, s6, s82
	s_cmp_lt_i32 s6, 0x100
	s_cbranch_scc0 .Lnc_done
; __device__ __forceinline__ unsigned cvt_pk_bf16(float lo, float hi) { unsigned r; asm volatile("v_cvt_pk_bf16_f32 %0, %1, %2" : "=v"(r) : "v"(lo), "v"(hi)); return r; }
; __device__ __forceinline__ void tr_jobs_part(const float* W, int K, int N, bf16_t* WT, float* sm, int tid, int rank, int nblk) {
;   const int cnt = (K >> 6) * (N >> 5); const int lane = tid & 63, wv = tid >> 6;
;   float* scr = sm + wv * (64 * 33);
; #pragma unroll 1
;   for (int t = rank * 8 + wv; t < cnt; t += nblk * 8) tr_item(W, K, N, WT, t, scr, lane);
; __device__ __forceinline__ void norm_rows(const float* src, int nrows, const float* gam, const float* sc, const float* sh, bf16_t* dst, int tid) {
;     ...
;       ss[q] = rsqrtf(wave_sum(s) * (1.0f / DM) + 1e-6f); }
; #pragma unroll
;     for (int j = 0; j < 8; ++j) {
;       const int c = 4 * (lane + 64 * j);
;       const f32x4 mul = *(const f32x4*)(gam + c) * (1.0f + *(const f32x4*)(sc + c)); const f32x4 add = *(const f32x4*)(sh + c);
; #pragma unroll
;       for (int q = 0; q < 4; ++q) if (ok[q]) {
;         const f32x4 h = v[q][j] * ss[q] * mul + add; u32x2 w; w.x = cvt_pk_bf16(h[0], h[1]); w.y = cvt_pk_bf16(h[2], h[3]);
;         ((u32x2*)(dst + (size_t)rr[q] * DM) + lane)[64 * j] = w;
;       }
;     }
	s_cmp_lt_i32 s7, 0x100
	s_cselect_b32 s10, s7, s11
	s_lshl_b32 s8, s10, 13
	s_add_u32 s8, s8, 0x1000
	s_mov_b32 s9, 0
	v_lshl_add_u64 v[246:247], v[134:135], 0, s[8:9]
	global_load_dwordx4 v[32:35], v[246:247], off offset:-4096
	global_load_dwordx4 v[36:39], v[246:247], off offset:-3072
	global_load_dwordx4 v[40:43], v[246:247], off offset:-2048
	global_load_dwordx4 v[44:47], v[246:247], off offset:-1024
	global_load_dwordx4 v[48:51], v[246:247], off
	global_load_dwordx4 v[52:55], v[246:247], off offset:1024
	global_load_dwordx4 v[56:59], v[246:247], off offset:2048
	global_load_dwordx4 v[60:63], v[246:247], off offset:3072
	s_add_i32 s7, s7, s82
	s_waitcnt vmcnt(48)
	v_pk_mul_f32 v[218:219], v[64:65], v[64:65]
	v_pk_fma_f32 v[218:219], v[66:67], v[66:67], v[218:219]
	v_pk_mul_f32 v[220:221], v[68:69], v[68:69]
	v_pk_fma_f32 v[220:221], v[70:71], v[70:71], v[220:221]
	v_pk_mul_f32 v[222:223], v[72:73], v[72:73]
	v_pk_fma_f32 v[222:223], v[74:75], v[74:75], v[222:223]
	v_pk_mul_f32 v[224:225], v[76:77], v[76:77]
	v_pk_fma_f32 v[224:225], v[78:79], v[78:79], v[224:225]
	v_pk_fma_f32 v[218:219], v[80:81], v[80:81], v[218:219]
	v_pk_fma_f32 v[218:219], v[82:83], v[82:83], v[218:219]
	v_pk_fma_f32 v[220:221], v[84:85], v[84:85], v[220:221]
	v_pk_fma_f32 v[220:221], v[86:87], v[86:87], v[220:221]
	v_pk_fma_f32 v[222:223], v[88:89], v[88:89], v[222:223]
	v_pk_fma_f32 v[222:223], v[90:91], v[90:91], v[222:223]
	v_pk_fma_f32 v[224:225], v[92:93], v[92:93], v[224:225]
	v_pk_fma_f32 v[224:225], v[94:95], v[94:95], v[224:225]
	v_pk_add_f32 v[218:219], v[218:219], v[220:221]
	v_pk_add_f32 v[222:223], v[222:223], v[224:225]
	v_pk_add_f32 v[218:219], v[218:219], v[222:223]
	v_add_f32_e32 v128, v218, v219
	ds_bpermute_b32 v129, v140, v128
	s_waitcnt lgkmcnt(0)
	v_add_f32_e32 v128, v128, v129
	ds_bpermute_b32 v129, v141, v128
	s_waitcnt lgkmcnt(0)
	v_add_f32_e32 v128, v128, v129
	ds_bpermute_b32 v129, v142, v128
	s_waitcnt lgkmcnt(0)
	v_add_f32_e32 v128, v128, v129
	ds_bpermute_b32 v129, v150, v128
	s_waitcnt lgkmcnt(0)
	v_add_f32_e32 v128, v128, v129
	ds_bpermute_b32 v129, v151, v128
	s_waitcnt lgkmcnt(0)
	v_add_f32_e32 v128, v128, v129
	ds_bpermute_b32 v129, v152, v128
	s_waitcnt lgkmcnt(0)
	v_add_f32_e32 v128, v128, v129
	v_fmamk_f32 v128, v128, 0x3a000000, v228
	v_mul_f32_e32 v129, 0x4b800000, v128
	v_cmp_gt_f32_e32 vcc, s67, v128
	s_nop 1
	v_cndmask_b32_e32 v128, v128, v129, vcc
	v_rsq_f32_e32 v128, v128
	s_nop 0
	v_mul_f32_e32 v129, 0x45800000, v128
	v_cndmask_b32_e32 v128, v128, v129, vcc
	s_lshl_b32 s8, s6, 12
	s_add_u32 s8, s8, 0x800
	s_mov_b32 s9, 0
	v_lshl_add_u64 v[230:231], v[136:137], 0, s[8:9]
	v_pk_mul_f32 v[64:65], v[64:65], v[128:129] op_sel_hi:[1,0]
	v_pk_fma_f32 v[64:65], v[64:65], v[154:155], v[186:187]
	v_pk_mul_f32 v[66:67], v[66:67], v[128:129] op_sel_hi:[1,0]
	v_pk_fma_f32 v[66:67], v[66:67], v[156:157], v[188:189]
	v_cvt_pk_bf16_f32 v64, v64, v65
	v_cvt_pk_bf16_f32 v65, v66, v67
	global_store_dwordx2 v[230:231], v[64:65], off offset:-2048
	v_pk_mul_f32 v[68:69], v[68:69], v[128:129] op_sel_hi:[1,0]
	v_pk_fma_f32 v[68:69], v[68:69], v[158:159], v[190:191]
	v_pk_mul_f32 v[70:71], v[70:71], v[128:129] op_sel_hi:[1,0]
	v_pk_fma_f32 v[70:71], v[70:71], v[160:161], v[192:193]
	v_cvt_pk_bf16_f32 v68, v68, v69
	v_cvt_pk_bf16_f32 v69, v70, v71
	global_store_dwordx2 v[230:231], v[68:69], off offset:-1536
	v_pk_mul_f32 v[72:73], v[72:73], v[128:129] op_sel_hi:[1,0]
	v_pk_fma_f32 v[72:73], v[72:73], v[162:163], v[194:195]
	v_pk_mul_f32 v[74:75], v[74:75], v[128:129] op_sel_hi:[1,0]
	v_pk_fma_f32 v[74:75], v[74:75], v[164:165], v[196:197]
	v_cvt_pk_bf16_f32 v72, v72, v73
	v_cvt_pk_bf16_f32 v73, v74, v75
	global_store_dwordx2 v[230:231], v[72:73], off offset:-1024
	v_pk_mul_f32 v[76:77], v[76:77], v[128:129] op_sel_hi:[1,0]
	v_pk_fma_f32 v[76:77], v[76:77], v[166:167], v[198:199]
	v_pk_mul_f32 v[78:79], v[78:79], v[128:129] op_sel_hi:[1,0]
	v_pk_fma_f32 v[78:79], v[78:79], v[168:169], v[200:201]
	v_cvt_pk_bf16_f32 v76, v76, v77
	v_cvt_pk_bf16_f32 v77, v78, v79
	global_store_dwordx2 v[230:231], v[76:77], off offset:-512
	v_pk_mul_f32 v[80:81], v[80:81], v[128:129] op_sel_hi:[1,0]
	v_pk_fma_f32 v[80:81], v[80:81], v[170:171], v[202:203]
	v_pk_mul_f32 v[82:83], v[82:83], v[128:129] op_sel_hi:[1,0]
	v_pk_fma_f32 v[82:83], v[82:83], v[172:173], v[204:205]
	v_cvt_pk_bf16_f32 v80, v80, v81
	v_cvt_pk_bf16_f32 v81, v82, v83
	global_store_dwordx2 v[230:231], v[80:81], off
	v_pk_mul_f32 v[84:85], v[84:85], v[128:129] op_sel_hi:[1,0]
	v_pk_fma_f32 v[84:85], v[84:85], v[174:175], v[206:207]
	v_pk_mul_f32 v[86:87], v[86:87], v[128:129] op_sel_hi:[1,0]
	v_pk_fma_f32 v[86:87], v[86:87], v[176:177], v[208:209]
	v_cvt_pk_bf16_f32 v84, v84, v85
	v_cvt_pk_bf16_f32 v85, v86, v87
	global_store_dwordx2 v[230:231], v[84:85], off offset:512
	v_pk_mul_f32 v[88:89], v[88:89], v[128:129] op_sel_hi:[1,0]
	v_pk_fma_f32 v[88:89], v[88:89], v[178:179], v[210:211]
	v_pk_mul_f32 v[90:91], v[90:91], v[128:129] op_sel_hi:[1,0]
	v_pk_fma_f32 v[90:91], v[90:91], v[180:181], v[212:213]
	v_cvt_pk_bf16_f32 v88, v88, v89
	v_cvt_pk_bf16_f32 v89, v90, v91
	global_store_dwordx2 v[230:231], v[88:89], off offset:1024
	v_pk_mul_f32 v[92:93], v[92:93], v[128:129] op_sel_hi:[1,0]
	v_pk_fma_f32 v[92:93], v[92:93], v[182:183], v[214:215]
	v_pk_mul_f32 v[94:95], v[94:95], v[128:129] op_sel_hi:[1,0]
	v_pk_fma_f32 v[94:95], v[94:95], v[184:185], v[216:217]
	v_cvt_pk_bf16_f32 v92, v92, v93
	v_cvt_pk_bf16_f32 v93, v94, v95
	global_store_dwordx2 v[230:231], v[92:93], off offset:1536
	s_add_i32 s6, s6, s82
	s_cmp_lt_i32 s6, 0x100
	s_cbranch_scc0 .Lnc_done
	s_branch .Lnc_loop
.Lnc_done:
	s_waitcnt vmcnt(0)
.LBB0_450:
	s_or_b64 exec, exec, s[4:5]
	s_cmp_lg_u32 s84, 11
	s_cbranch_scc1 .LBB0_455
	s_movk_i32 s2, 0x1600
	v_cmp_gt_i32_e32 vcc, s2, v132
	s_and_saveexec_b64 s[2:3], vcc
	s_movk_i32 s7, 0x15ff
	s_cbranch_execz .LBB0_454
	v_readlane_b32 s4, v254, 9
	v_readlane_b32 s5, v254, 10
	s_movk_i32 s6, 0x2100
	s_load_dwordx2 s[4:5], s[4:5], 0xf8
	v_mul_lo_u32 v0, v145, s6
	v_add_u32_e32 v4, 0, v0
	v_bfe_u32 v12, v229, 5, 1
	v_lshlrev_b32_e32 v0, 2, v229
	v_and_b32_e32 v138, 0x7c, v0
	v_mul_u32_u24_e32 v2, 0x84, v12
	v_add3_u32 v13, v4, v2, v138
	v_lshlrev_b32_e32 v2, 3, v229
	v_and_b32_e32 v2, 56, v2
	s_waitcnt lgkmcnt(0)
	v_lshl_add_u64 v[0:1], s[4:5], 0, v[138:139]
	v_lshlrev_b32_e32 v138, 1, v2
	v_bfe_u32 v14, v229, 3, 3
	v_mul_u32_u24_e32 v5, 0x84, v2
	v_lshl_add_u64 v[2:3], s[0:1], 0, v[138:139]
	s_mov_b64 s[0:1], 0x5600000
	s_mov_b64 s[4:5], 0x2c00000
	v_lshl_add_u64 v[2:3], v[2:3], 0, s[0:1]
	v_lshlrev_b32_e32 v6, 2, v14
	v_readlane_b32 s0, v253, 34
	v_lshl_add_u64 v[0:1], v[0:1], 0, s[4:5]
	v_add3_u32 v15, v4, v5, v6
	v_lshl_add_u32 v16, v145, 5, s0
	s_mov_b64 s[0:1], 0
